# cache policy: PEER reads each token's H row (read once) with non-temporal loads
# baseline (speedup 1.0000x reference)
.LBB0_732:
	s_mov_b64 s[36:37], s[16:17]
	v_mov_b32_e32 v17, v214
	v_lshl_add_u32 v12, v223, 9, s62
	v_add_u32_e32 v180, s63, v223
	v_ashrrev_i32_e32 v181, 31, v180
	v_lshl_add_u32 v0, v17, 2, v12
	ds_read2st64_b32 v[150:151], v0 offset0:160 offset1:161
	v_lshlrev_b64 v[0:1], 12, v[180:181]
	v_lshl_add_u64 v[0:1], s[36:37], 0, v[0:1]
	s_mov_b64 s[10:11], 0x1b74b200
	v_lshl_add_u64 v[178:179], v[0:1], 0, s[10:11]
	v_lshlrev_b32_e32 v0, 5, v17
	v_ashrrev_i32_e32 v1, 31, v0
	v_lshl_add_u64 v[0:1], v[0:1], 1, v[178:179]
	global_load_dwordx4 v[2:5], v[0:1], off offset:48 nt
	global_load_dwordx4 v[6:9], v[0:1], off offset:32 nt
	global_load_dwordx4 v[18:21], v[0:1], off offset:16 nt
	global_load_dwordx4 v[22:25], v[0:1], off nt
	v_mov_b32_e32 v0, v16
	v_lshl_add_u32 v10, v17, 4, v216
	v_and_b32_e32 v158, 15, v17
	s_add_u32 s10, s36, s20
	s_addc_u32 s11, s37, s21
	s_add_u32 s12, s10, 0x9a04000
	s_addc_u32 s13, s11, 0
	v_and_b32_e32 v152, -16, v17
	v_ashrrev_i32_e32 v153, 31, v152
	v_lshlrev_b32_e32 v224, 3, v17
	v_and_b32_e32 v154, 3, v17
	s_mov_b64 s[0:1], 0xda04000
	s_waitcnt vmcnt(3)
	v_lshlrev_b32_e32 v53, 16, v2
	v_and_b32_e32 v55, 0xffff0000, v2
	v_lshlrev_b32_e32 v57, 16, v3
	s_waitcnt vmcnt(0)
	v_lshlrev_b32_e32 v1, 16, v22
	v_and_b32_e32 v13, 0xffff0000, v22
	v_mul_f32_e32 v11, 0x3e800000, v1
	v_mul_f32_e32 v14, 0x3e800000, v13
	v_lshlrev_b32_e32 v15, 16, v23
	v_and_b32_e32 v23, 0xffff0000, v23
	v_mul_f32_e32 v22, 0x3e800000, v15
	v_mul_f32_e32 v26, 0x3e800000, v23
	v_lshlrev_b32_e32 v27, 16, v24
	v_and_b32_e32 v24, 0xffff0000, v24
	v_cvt_scalef32_pk_fp4_f32 v0, v11, v14, 1.0
	v_mul_f32_e32 v28, 0x3e800000, v27
	v_mul_f32_e32 v29, 0x3e800000, v24
	v_lshlrev_b32_e32 v30, 16, v25
	v_and_b32_e32 v25, 0xffff0000, v25
	v_cvt_scalef32_pk_fp4_f32 v0, v22, v26, 1.0 op_sel:[0,0,1,0]
	v_mul_f32_e32 v31, 0x3e800000, v30
	v_mul_f32_e32 v32, 0x3e800000, v25
	v_cvt_scalef32_pk_fp4_f32 v0, v28, v29, 1.0 op_sel:[0,0,0,1]
	v_lshlrev_b32_e32 v11, 16, v18
	v_cvt_scalef32_pk_fp4_f32 v0, v31, v32, 1.0 op_sel:[0,0,1,1]
	v_and_b32_e32 v18, 0xffff0000, v18
	v_and_b32_e32 v59, 0xffff0000, v3
	v_cvt_scalef32_pk_f32_fp4 v[2:3], v0, 1.0
	v_mul_f32_e32 v14, 0x3e800000, v11
	v_mul_f32_e32 v22, 0x3e800000, v18
	v_lshlrev_b32_e32 v26, 16, v19
	v_and_b32_e32 v19, 0xffff0000, v19
	v_fma_f32 v69, v1, s87, -v2
	v_mov_b32_e32 v1, v16
	v_mul_f32_e32 v28, 0x3e800000, v26
	v_mul_f32_e32 v29, 0x3e800000, v19
	v_lshlrev_b32_e32 v31, 16, v20
	v_and_b32_e32 v20, 0xffff0000, v20
	v_cvt_scalef32_pk_fp4_f32 v1, v14, v22, 1.0
	v_mul_f32_e32 v32, 0x3e800000, v31
	v_mul_f32_e32 v33, 0x3e800000, v20
	v_lshlrev_b32_e32 v34, 16, v21
	v_and_b32_e32 v21, 0xffff0000, v21
	v_cvt_scalef32_pk_fp4_f32 v1, v28, v29, 1.0 op_sel:[0,0,1,0]
	v_mul_f32_e32 v35, 0x3e800000, v34
	v_mul_f32_e32 v36, 0x3e800000, v21
	v_cvt_scalef32_pk_fp4_f32 v1, v32, v33, 1.0 op_sel:[0,0,0,1]
	v_lshlrev_b32_e32 v37, 16, v6
	v_cvt_scalef32_pk_fp4_f32 v1, v35, v36, 1.0 op_sel:[0,0,1,1]
	v_and_b32_e32 v39, 0xffff0000, v6
	v_fma_f32 v13, v13, s87, -v3
	v_cvt_scalef32_pk_f32_fp4 v[2:3], v1, 1.0
	v_mul_f32_e32 v38, 0x3e800000, v37
	v_mul_f32_e32 v40, 0x3e800000, v39
	v_lshlrev_b32_e32 v41, 16, v7
	v_and_b32_e32 v43, 0xffff0000, v7
	v_mul_f32_e32 v54, 0x3e800000, v53
	v_mul_f32_e32 v56, 0x3e800000, v55
	v_fma_f32 v11, v11, s87, -v2
	v_fma_f32 v18, v18, s87, -v3
	v_mov_b32_e32 v2, v16
	v_mov_b32_e32 v3, v16
	v_mul_f32_e32 v42, 0x3e800000, v41
	v_mul_f32_e32 v44, 0x3e800000, v43
	v_lshlrev_b32_e32 v45, 16, v8
	v_and_b32_e32 v47, 0xffff0000, v8
	v_mul_f32_e32 v58, 0x3e800000, v57
	v_mul_f32_e32 v60, 0x3e800000, v59
	v_lshlrev_b32_e32 v61, 16, v4
	v_and_b32_e32 v63, 0xffff0000, v4
	v_cvt_scalef32_pk_fp4_f32 v2, v38, v40, 1.0
	v_cvt_scalef32_pk_fp4_f32 v3, v54, v56, 1.0
	v_mul_f32_e32 v46, 0x3e800000, v45
	v_mul_f32_e32 v48, 0x3e800000, v47
	v_lshlrev_b32_e32 v49, 16, v9
	v_and_b32_e32 v51, 0xffff0000, v9
	v_mul_f32_e32 v62, 0x3e800000, v61
	v_mul_f32_e32 v64, 0x3e800000, v63
	v_lshlrev_b32_e32 v65, 16, v5
	v_and_b32_e32 v67, 0xffff0000, v5
	v_cvt_scalef32_pk_fp4_f32 v2, v42, v44, 1.0 op_sel:[0,0,1,0]
	v_cvt_scalef32_pk_fp4_f32 v3, v58, v60, 1.0 op_sel:[0,0,1,0]
	v_mul_f32_e32 v50, 0x3e800000, v49
	v_mul_f32_e32 v52, 0x3e800000, v51
	v_mul_f32_e32 v66, 0x3e800000, v65
	v_mul_f32_e32 v68, 0x3e800000, v67
	v_cvt_scalef32_pk_fp4_f32 v2, v46, v48, 1.0 op_sel:[0,0,0,1]
	v_cvt_scalef32_pk_fp4_f32 v3, v62, v64, 1.0 op_sel:[0,0,0,1]
	v_cvt_scalef32_pk_f32_fp4 v[4:5], v0, 1.0 op_sel:[1,0,0]
	v_cvt_scalef32_pk_fp4_f32 v2, v50, v52, 1.0 op_sel:[0,0,1,1]
	v_cvt_scalef32_pk_fp4_f32 v3, v66, v68, 1.0 op_sel:[0,0,1,1]
	v_cvt_scalef32_pk_f32_fp4 v[6:7], v0, 1.0 op_sel:[0,1,0]
	v_cvt_scalef32_pk_f32_fp4 v[8:9], v0, 1.0 op_sel:[1,1,0]
	v_mul_f32_e32 v70, 4.0, v69
	v_mul_f32_e32 v71, 4.0, v13
	v_fma_f32 v72, v15, s87, -v4
	v_fma_f32 v23, v23, s87, -v5
	v_cvt_scalef32_pk_f32_fp4 v[4:5], v1, 1.0 op_sel:[1,0,0]
	ds_write_b128 v10, v[0:3]
	v_mov_b32_e32 v0, v16
	v_mul_f32_e32 v73, 4.0, v72
	v_mul_f32_e32 v74, 4.0, v23
	v_fma_f32 v27, v27, s87, -v6
	v_fma_f32 v24, v24, s87, -v7
	v_fma_f32 v30, v30, s87, -v8
	v_fma_f32 v25, v25, s87, -v9
	v_cvt_scalef32_pk_f32_fp4 v[6:7], v1, 1.0 op_sel:[0,1,0]
	v_cvt_scalef32_pk_f32_fp4 v[8:9], v1, 1.0 op_sel:[1,1,0]
	v_mul_f32_e32 v22, 4.0, v11
	v_mul_f32_e32 v28, 4.0, v18
	v_fma_f32 v26, v26, s87, -v4
	v_fma_f32 v19, v19, s87, -v5
	v_cvt_scalef32_pk_fp4_f32 v0, v70, v71, 1.0
	v_mov_b32_e32 v1, v16
	v_mul_f32_e32 v75, 4.0, v27
	v_mul_f32_e32 v76, 4.0, v24
	v_mul_f32_e32 v29, 4.0, v26
	v_mul_f32_e32 v32, 4.0, v19
	v_fma_f32 v31, v31, s87, -v6
	v_fma_f32 v20, v20, s87, -v7
	v_cvt_scalef32_pk_fp4_f32 v0, v73, v74, 1.0 op_sel:[0,0,1,0]
	v_cvt_scalef32_pk_fp4_f32 v1, v22, v28, 1.0
	v_mul_f32_e32 v77, 4.0, v30
	v_mul_f32_e32 v78, 4.0, v25
	v_mul_f32_e32 v33, 4.0, v31
	v_mul_f32_e32 v35, 4.0, v20
	v_fma_f32 v34, v34, s87, -v8
	v_fma_f32 v21, v21, s87, -v9
	v_cvt_scalef32_pk_fp4_f32 v0, v75, v76, 1.0 op_sel:[0,0,0,1]
	v_cvt_scalef32_pk_fp4_f32 v1, v29, v32, 1.0 op_sel:[0,0,1,0]
	v_mul_f32_e32 v36, 4.0, v34
	v_mul_f32_e32 v79, 4.0, v21
	v_cvt_scalef32_pk_f32_fp4 v[4:5], v2, 1.0
	v_cvt_scalef32_pk_f32_fp4 v[6:7], v2, 1.0 op_sel:[1,0,0]
	v_cvt_scalef32_pk_f32_fp4 v[8:9], v2, 1.0 op_sel:[0,1,0]
	v_cvt_scalef32_pk_f32_fp4 v[14:15], v2, 1.0 op_sel:[1,1,0]
	v_cvt_scalef32_pk_fp4_f32 v0, v77, v78, 1.0 op_sel:[0,0,1,1]
	v_cvt_scalef32_pk_fp4_f32 v1, v33, v35, 1.0 op_sel:[0,0,0,1]
	v_fma_f32 v37, v37, s87, -v4
	v_fma_f32 v39, v39, s87, -v5
	v_fma_f32 v41, v41, s87, -v6
	v_fma_f32 v43, v43, s87, -v7
	v_fma_f32 v45, v45, s87, -v8
	v_fma_f32 v47, v47, s87, -v9
	v_fma_f32 v49, v49, s87, -v14
	v_fma_f32 v51, v51, s87, -v15
	v_cvt_scalef32_pk_f32_fp4 v[4:5], v3, 1.0
	v_cvt_scalef32_pk_f32_fp4 v[6:7], v3, 1.0 op_sel:[1,0,0]
	v_cvt_scalef32_pk_f32_fp4 v[8:9], v3, 1.0 op_sel:[0,1,0]
	v_cvt_scalef32_pk_f32_fp4 v[14:15], v3, 1.0 op_sel:[1,1,0]
	v_cvt_scalef32_pk_f32_fp4 v[2:3], v0, 1.0
	v_cvt_scalef32_pk_fp4_f32 v1, v36, v79, 1.0 op_sel:[0,0,1,1]
	v_fma_f32 v53, v53, s87, -v4
	v_fma_f32 v55, v55, s87, -v5
	v_fma_f32 v69, v69, 4.0, -v2
	v_fma_f32 v13, v13, 4.0, -v3
	v_cvt_scalef32_pk_f32_fp4 v[2:3], v1, 1.0
	v_mul_f32_e32 v38, 4.0, v37
	v_mul_f32_e32 v40, 4.0, v39
	v_mul_f32_e32 v54, 4.0, v53
	v_mul_f32_e32 v56, 4.0, v55
	v_fma_f32 v57, v57, s87, -v6
	v_fma_f32 v59, v59, s87, -v7
	v_fma_f32 v11, v11, 4.0, -v2
	v_fma_f32 v18, v18, 4.0, -v3
	v_mov_b32_e32 v2, v16
	v_mov_b32_e32 v3, v16
	v_mul_f32_e32 v42, 4.0, v41
	v_mul_f32_e32 v44, 4.0, v43
	v_mul_f32_e32 v58, 4.0, v57
	v_mul_f32_e32 v60, 4.0, v59
	v_fma_f32 v61, v61, s87, -v8
	v_fma_f32 v63, v63, s87, -v9
	v_cvt_scalef32_pk_fp4_f32 v2, v38, v40, 1.0
	v_cvt_scalef32_pk_fp4_f32 v3, v54, v56, 1.0
	v_mul_f32_e32 v46, 4.0, v45
	v_mul_f32_e32 v48, 4.0, v47
	v_mul_f32_e32 v62, 4.0, v61
	v_mul_f32_e32 v64, 4.0, v63
	v_fma_f32 v65, v65, s87, -v14
	v_fma_f32 v67, v67, s87, -v15
	v_cvt_scalef32_pk_fp4_f32 v2, v42, v44, 1.0 op_sel:[0,0,1,0]
	v_cvt_scalef32_pk_fp4_f32 v3, v58, v60, 1.0 op_sel:[0,0,1,0]
	v_mul_f32_e32 v50, 4.0, v49
	v_mul_f32_e32 v52, 4.0, v51
	v_mul_f32_e32 v66, 4.0, v65
	v_mul_f32_e32 v68, 4.0, v67
	v_cvt_scalef32_pk_fp4_f32 v2, v46, v48, 1.0 op_sel:[0,0,0,1]
	v_cvt_scalef32_pk_fp4_f32 v3, v62, v64, 1.0 op_sel:[0,0,0,1]
	v_cvt_scalef32_pk_f32_fp4 v[4:5], v0, 1.0 op_sel:[1,0,0]
	v_cvt_scalef32_pk_fp4_f32 v2, v50, v52, 1.0 op_sel:[0,0,1,1]
	v_cvt_scalef32_pk_fp4_f32 v3, v66, v68, 1.0 op_sel:[0,0,1,1]
	v_cvt_scalef32_pk_f32_fp4 v[6:7], v0, 1.0 op_sel:[0,1,0]
	v_cvt_scalef32_pk_f32_fp4 v[8:9], v0, 1.0 op_sel:[1,1,0]
	v_mul_f32_e32 v70, 4.0, v69
	v_mul_f32_e32 v71, 4.0, v13
	v_fma_f32 v72, v72, 4.0, -v4
	v_fma_f32 v23, v23, 4.0, -v5
	ds_write_b128 v10, v[0:3] offset:1024
	v_mov_b32_e32 v0, v16
	v_mul_f32_e32 v73, 4.0, v72
	v_mul_f32_e32 v74, 4.0, v23
	v_fma_f32 v27, v27, 4.0, -v6
	v_fma_f32 v24, v24, 4.0, -v7
	v_cvt_scalef32_pk_fp4_f32 v0, v70, v71, 1.0
	v_mul_f32_e32 v75, 4.0, v27
	v_mul_f32_e32 v76, 4.0, v24
	v_fma_f32 v30, v30, 4.0, -v8
	v_fma_f32 v25, v25, 4.0, -v9
	v_cvt_scalef32_pk_fp4_f32 v0, v73, v74, 1.0 op_sel:[0,0,1,0]
	v_mul_f32_e32 v77, 4.0, v30
	v_mul_f32_e32 v78, 4.0, v25
	v_cvt_scalef32_pk_f32_fp4 v[4:5], v1, 1.0 op_sel:[1,0,0]
	v_cvt_scalef32_pk_f32_fp4 v[6:7], v1, 1.0 op_sel:[0,1,0]
	v_cvt_scalef32_pk_f32_fp4 v[8:9], v1, 1.0 op_sel:[1,1,0]
	v_cvt_scalef32_pk_fp4_f32 v0, v75, v76, 1.0 op_sel:[0,0,0,1]
	v_fma_f32 v26, v26, 4.0, -v4
	v_fma_f32 v19, v19, 4.0, -v5
	v_fma_f32 v31, v31, 4.0, -v6
	v_fma_f32 v20, v20, 4.0, -v7
	v_fma_f32 v34, v34, 4.0, -v8
	v_fma_f32 v21, v21, 4.0, -v9
	v_cvt_scalef32_pk_f32_fp4 v[4:5], v2, 1.0
	v_cvt_scalef32_pk_f32_fp4 v[6:7], v2, 1.0 op_sel:[1,0,0]
	v_cvt_scalef32_pk_f32_fp4 v[8:9], v2, 1.0 op_sel:[0,1,0]
	v_cvt_scalef32_pk_f32_fp4 v[14:15], v2, 1.0 op_sel:[1,1,0]
	v_cvt_scalef32_pk_fp4_f32 v0, v77, v78, 1.0 op_sel:[0,0,1,1]
	v_fma_f32 v37, v37, 4.0, -v4
	v_fma_f32 v39, v39, 4.0, -v5
	v_fma_f32 v41, v41, 4.0, -v6
	v_fma_f32 v43, v43, 4.0, -v7
	v_fma_f32 v45, v45, 4.0, -v8
	v_fma_f32 v47, v47, 4.0, -v9
	v_fma_f32 v49, v49, 4.0, -v14
	v_fma_f32 v51, v51, 4.0, -v15
	v_cvt_scalef32_pk_f32_fp4 v[4:5], v3, 1.0
	v_cvt_scalef32_pk_f32_fp4 v[6:7], v3, 1.0 op_sel:[1,0,0]
	v_cvt_scalef32_pk_f32_fp4 v[8:9], v3, 1.0 op_sel:[0,1,0]
	v_cvt_scalef32_pk_f32_fp4 v[14:15], v3, 1.0 op_sel:[1,1,0]
	v_cvt_scalef32_pk_f32_fp4 v[2:3], v0, 1.0
	v_fma_f32 v1, v69, 4.0, -v2
	v_fma_f32 v53, v53, 4.0, -v4
	v_fma_f32 v55, v55, 4.0, -v5
	v_cvt_scalef32_pk_f32_fp4 v[4:5], v0, 1.0 op_sel:[1,0,0]
	v_mul_f32_e32 v69, 4.0, v1
	v_fma_f32 v1, v13, 4.0, -v3
	v_mul_f32_e32 v13, 4.0, v1
	v_fma_f32 v1, v72, 4.0, -v4
	v_fma_f32 v57, v57, 4.0, -v6
	v_fma_f32 v59, v59, 4.0, -v7
	v_cvt_scalef32_pk_f32_fp4 v[6:7], v0, 1.0 op_sel:[0,1,0]
	v_mul_f32_e32 v70, 4.0, v1
	v_fma_f32 v1, v23, 4.0, -v5
	v_mul_f32_e32 v23, 4.0, v1
	v_fma_f32 v1, v27, 4.0, -v6
	v_fma_f32 v61, v61, 4.0, -v8
	v_fma_f32 v63, v63, 4.0, -v9
	v_cvt_scalef32_pk_f32_fp4 v[8:9], v0, 1.0 op_sel:[1,1,0]
	v_mul_f32_e32 v27, 4.0, v1
	v_fma_f32 v1, v24, 4.0, -v7
	v_mul_f32_e32 v24, 4.0, v1
	v_fma_f32 v1, v30, 4.0, -v8
	v_mul_f32_e32 v30, 4.0, v1
	v_fma_f32 v1, v25, 4.0, -v9
	v_mul_f32_e32 v22, 4.0, v11
	v_mul_f32_e32 v28, 4.0, v18
	v_mul_f32_e32 v25, 4.0, v1
	v_mov_b32_e32 v1, v16
	v_mul_f32_e32 v29, 4.0, v26
	v_mul_f32_e32 v32, 4.0, v19
	v_cvt_scalef32_pk_fp4_f32 v1, v22, v28, 1.0
	v_mul_f32_e32 v33, 4.0, v31
	v_mul_f32_e32 v35, 4.0, v20
	v_cvt_scalef32_pk_fp4_f32 v1, v29, v32, 1.0 op_sel:[0,0,1,0]
	v_mul_f32_e32 v36, 4.0, v34
	v_mul_f32_e32 v79, 4.0, v21
	v_cvt_scalef32_pk_fp4_f32 v1, v33, v35, 1.0 op_sel:[0,0,0,1]
	v_mul_f32_e32 v38, 4.0, v37
	v_cvt_scalef32_pk_fp4_f32 v1, v36, v79, 1.0 op_sel:[0,0,1,1]
	v_mul_f32_e32 v40, 4.0, v39
	v_cvt_scalef32_pk_f32_fp4 v[2:3], v1, 1.0
	v_fma_f32 v2, v11, 4.0, -v2
	v_cvt_scalef32_pk_f32_fp4 v[4:5], v1, 1.0 op_sel:[1,0,0]
	v_mul_f32_e32 v11, 4.0, v2
	v_fma_f32 v2, v18, 4.0, -v3
	v_mul_f32_e32 v18, 4.0, v2
	v_fma_f32 v2, v26, 4.0, -v4
	v_cvt_scalef32_pk_f32_fp4 v[6:7], v1, 1.0 op_sel:[0,1,0]
	v_mul_f32_e32 v22, 4.0, v2
	v_fma_f32 v2, v19, 4.0, -v5
	v_mul_f32_e32 v19, 4.0, v2
	v_fma_f32 v2, v31, 4.0, -v6
	v_cvt_scalef32_pk_f32_fp4 v[8:9], v1, 1.0 op_sel:[1,1,0]
	v_mul_f32_e32 v26, 4.0, v2
	v_fma_f32 v2, v20, 4.0, -v7
	v_mul_f32_e32 v20, 4.0, v2
	v_fma_f32 v2, v34, 4.0, -v8
	v_mul_f32_e32 v28, 4.0, v2
	v_fma_f32 v2, v21, 4.0, -v9
	v_mul_f32_e32 v21, 4.0, v2
	v_mov_b32_e32 v2, v16
	v_mul_f32_e32 v42, 4.0, v41
	v_mul_f32_e32 v44, 4.0, v43
	v_cvt_scalef32_pk_fp4_f32 v2, v38, v40, 1.0
	v_mul_f32_e32 v46, 4.0, v45
	v_mul_f32_e32 v48, 4.0, v47
	v_cvt_scalef32_pk_fp4_f32 v2, v42, v44, 1.0 op_sel:[0,0,1,0]
	v_mul_f32_e32 v50, 4.0, v49
	v_mul_f32_e32 v52, 4.0, v51
	v_cvt_scalef32_pk_fp4_f32 v2, v46, v48, 1.0 op_sel:[0,0,0,1]
	v_fma_f32 v65, v65, 4.0, -v14
	v_cvt_scalef32_pk_fp4_f32 v2, v50, v52, 1.0 op_sel:[0,0,1,1]
	v_fma_f32 v67, v67, 4.0, -v15
	v_cvt_scalef32_pk_f32_fp4 v[4:5], v2, 1.0
	v_fma_f32 v3, v37, 4.0, -v4
	v_cvt_scalef32_pk_f32_fp4 v[6:7], v2, 1.0 op_sel:[1,0,0]
	v_mul_f32_e32 v29, 4.0, v3
	v_fma_f32 v3, v39, 4.0, -v5
	v_mul_f32_e32 v31, 4.0, v3
	v_fma_f32 v3, v41, 4.0, -v6
	v_cvt_scalef32_pk_f32_fp4 v[8:9], v2, 1.0 op_sel:[0,1,0]
	v_mul_f32_e32 v32, 4.0, v3
	v_fma_f32 v3, v43, 4.0, -v7
	v_mul_f32_e32 v33, 4.0, v3
	v_fma_f32 v3, v45, 4.0, -v8
	v_cvt_scalef32_pk_f32_fp4 v[14:15], v2, 1.0 op_sel:[1,1,0]
	v_mul_f32_e32 v34, 4.0, v3
	v_fma_f32 v3, v47, 4.0, -v9
	v_mul_f32_e32 v35, 4.0, v3
	v_fma_f32 v3, v49, 4.0, -v14
	v_mul_f32_e32 v36, 4.0, v3
	v_fma_f32 v3, v51, 4.0, -v15
	v_mul_f32_e32 v54, 4.0, v53
	v_mul_f32_e32 v56, 4.0, v55
	v_mul_f32_e32 v37, 4.0, v3
	v_mov_b32_e32 v3, v16
	v_mul_f32_e32 v58, 4.0, v57
	v_mul_f32_e32 v60, 4.0, v59
	v_cvt_scalef32_pk_fp4_f32 v3, v54, v56, 1.0
	v_mul_f32_e32 v62, 4.0, v61
	v_mul_f32_e32 v64, 4.0, v63
	v_cvt_scalef32_pk_fp4_f32 v3, v58, v60, 1.0 op_sel:[0,0,1,0]
	v_mul_f32_e32 v66, 4.0, v65
	v_mul_f32_e32 v68, 4.0, v67
	v_cvt_scalef32_pk_fp4_f32 v3, v62, v64, 1.0 op_sel:[0,0,0,1]
	s_nop 0
	v_cvt_scalef32_pk_fp4_f32 v3, v66, v68, 1.0 op_sel:[0,0,1,1]
	ds_write_b128 v10, v[0:3] offset:2048
	v_cvt_scalef32_pk_f32_fp4 v[4:5], v3, 1.0
	v_cvt_scalef32_pk_f32_fp4 v[6:7], v3, 1.0 op_sel:[1,0,0]
	v_fma_f32 v4, v53, 4.0, -v4
	v_fma_f32 v5, v55, 4.0, -v5
	v_cvt_scalef32_pk_f32_fp4 v[8:9], v3, 1.0 op_sel:[0,1,0]
	v_cvt_scalef32_pk_f32_fp4 v[14:15], v3, 1.0 op_sel:[1,1,0]
	v_mul_f32_e32 v4, 4.0, v4
	v_mul_f32_e32 v5, 4.0, v5
	v_fma_f32 v6, v57, 4.0, -v6
	v_fma_f32 v7, v59, 4.0, -v7
	v_mov_b32_e32 v0, v16
	v_mov_b32_e32 v1, v16
	v_mov_b32_e32 v2, v16
	v_mov_b32_e32 v3, v16
	v_mul_f32_e32 v6, 4.0, v6
	v_mul_f32_e32 v7, 4.0, v7
	v_fma_f32 v8, v61, 4.0, -v8
	v_fma_f32 v9, v63, 4.0, -v9
	v_cvt_scalef32_pk_fp4_f32 v0, v69, v13, 1.0
	v_cvt_scalef32_pk_fp4_f32 v1, v11, v18, 1.0
	v_cvt_scalef32_pk_fp4_f32 v2, v29, v31, 1.0
	v_cvt_scalef32_pk_fp4_f32 v3, v4, v5, 1.0
	v_mul_f32_e32 v8, 4.0, v8
	v_mul_f32_e32 v9, 4.0, v9
	v_fma_f32 v14, v65, 4.0, -v14
	v_fma_f32 v15, v67, 4.0, -v15
	v_cvt_scalef32_pk_fp4_f32 v0, v70, v23, 1.0 op_sel:[0,0,1,0]
	v_cvt_scalef32_pk_fp4_f32 v1, v22, v19, 1.0 op_sel:[0,0,1,0]
	v_cvt_scalef32_pk_fp4_f32 v2, v32, v33, 1.0 op_sel:[0,0,1,0]
	v_cvt_scalef32_pk_fp4_f32 v3, v6, v7, 1.0 op_sel:[0,0,1,0]
	v_mul_f32_e32 v14, 4.0, v14
	v_mul_f32_e32 v15, 4.0, v15
	v_cvt_scalef32_pk_fp4_f32 v0, v27, v24, 1.0 op_sel:[0,0,0,1]
	v_cvt_scalef32_pk_fp4_f32 v1, v26, v20, 1.0 op_sel:[0,0,0,1]
	v_cvt_scalef32_pk_fp4_f32 v2, v34, v35, 1.0 op_sel:[0,0,0,1]
	v_cvt_scalef32_pk_fp4_f32 v3, v8, v9, 1.0 op_sel:[0,0,0,1]
	v_cvt_scalef32_pk_fp4_f32 v0, v30, v25, 1.0 op_sel:[0,0,1,1]
	v_cvt_scalef32_pk_fp4_f32 v1, v28, v21, 1.0 op_sel:[0,0,1,1]
	v_cvt_scalef32_pk_fp4_f32 v2, v36, v37, 1.0 op_sel:[0,0,1,1]
	v_cvt_scalef32_pk_fp4_f32 v3, v14, v15, 1.0 op_sel:[0,0,1,1]
	ds_write_b128 v10, v[0:3] offset:3072
	v_lshl_add_u32 v0, v158, 2, v12
	v_add_u32_e32 v13, 0x8000, v0
	ds_read2_b32 v[2:3], v13 offset1:16
	ds_read2_b32 v[6:7], v13 offset0:32 offset1:48
	ds_read2_b32 v[10:11], v13 offset0:64 offset1:80
	s_waitcnt lgkmcnt(2)
	v_ashrrev_i32_e32 v5, 31, v3
	v_mov_b32_e32 v4, v3
	s_waitcnt lgkmcnt(1)
	v_ashrrev_i32_e32 v9, 31, v7
	v_mov_b32_e32 v8, v7
	s_waitcnt lgkmcnt(0)
	v_ashrrev_i32_e32 v15, 31, v11
	v_mov_b32_e32 v14, v11
	v_ashrrev_i32_e32 v1, 31, v2
	v_mov_b32_e32 v0, v2
	v_lshlrev_b64 v[2:3], 10, v[4:5]
	v_ashrrev_i32_e32 v5, 31, v6
	v_mov_b32_e32 v4, v6
	v_lshlrev_b64 v[6:7], 10, v[8:9]
	v_ashrrev_i32_e32 v9, 31, v10
	v_mov_b32_e32 v8, v10
	v_lshlrev_b64 v[10:11], 10, v[14:15]
	ds_read2_b32 v[14:15], v13 offset0:96 offset1:112
	v_lshlrev_b64 v[0:1], 10, v[0:1]
	v_lshl_add_u64 v[0:1], s[12:13], 0, v[0:1]
	v_lshlrev_b64 v[4:5], 10, v[4:5]
	v_lshlrev_b64 v[8:9], 10, v[8:9]
	s_waitcnt lgkmcnt(0)
	v_ashrrev_i32_e32 v19, 31, v14
	v_mov_b32_e32 v18, v14
	v_ashrrev_i32_e32 v21, 31, v15
	v_mov_b32_e32 v20, v15
	v_lshlrev_b64 v[18:19], 10, v[18:19]
	v_lshlrev_b64 v[14:15], 10, v[20:21]
	v_lshl_add_u64 v[0:1], v[0:1], 0, v[152:153]
	v_lshl_add_u64 v[2:3], s[12:13], 0, v[2:3]
	v_lshl_add_u64 v[4:5], s[12:13], 0, v[4:5]
	v_lshl_add_u64 v[6:7], s[12:13], 0, v[6:7]
	v_lshl_add_u64 v[8:9], s[12:13], 0, v[8:9]
	v_lshl_add_u64 v[10:11], s[12:13], 0, v[10:11]
	v_lshl_add_u64 v[18:19], s[12:13], 0, v[18:19]
	v_lshl_add_u64 v[14:15], s[12:13], 0, v[14:15]
	v_lshl_add_u64 v[2:3], v[2:3], 0, v[152:153]
	v_lshl_add_u64 v[4:5], v[4:5], 0, v[152:153]
	v_lshl_add_u64 v[6:7], v[6:7], 0, v[152:153]
	v_lshl_add_u64 v[8:9], v[8:9], 0, v[152:153]
	v_lshl_add_u64 v[10:11], v[10:11], 0, v[152:153]
	v_lshl_add_u64 v[18:19], v[18:19], 0, v[152:153]
	v_lshl_add_u64 v[20:21], v[14:15], 0, v[152:153]
	global_load_dwordx4 v[22:25], v[0:1], off
	global_load_dwordx4 v[26:29], v[0:1], off offset:64
	global_load_dwordx4 v[30:33], v[2:3], off
	global_load_dwordx4 v[34:37], v[2:3], off offset:64
	global_load_dwordx4 v[38:41], v[4:5], off
	global_load_dwordx4 v[42:45], v[4:5], off offset:64
	global_load_dwordx4 v[46:49], v[6:7], off
	global_load_dwordx4 v[56:59], v[6:7], off offset:64
	global_load_dwordx4 v[60:63], v[8:9], off
	global_load_dwordx4 v[64:67], v[8:9], off offset:64
	global_load_dwordx4 v[72:75], v[10:11], off
	global_load_dwordx4 v[76:79], v[10:11], off offset:64
	global_load_dwordx4 v[80:83], v[18:19], off
	global_load_dwordx4 v[84:87], v[18:19], off offset:64
	global_load_dwordx4 v[88:91], v[20:21], off
	global_load_dwordx4 v[92:95], v[20:21], off offset:64
	v_lshlrev_b32_e32 v14, 4, v158
	v_mov_b32_e32 v15, v16
	v_and_b32_e32 v153, 0xffffff80, v224
	v_lshlrev_b32_e32 v13, 10, v154
	v_lshl_add_u64 v[14:15], s[10:11], 0, v[14:15]
	v_add_u32_e32 v225, v12, v153
	v_add3_u32 v70, v216, v13, v152
	v_lshl_add_u64 v[182:183], v[14:15], 0, s[0:1]
	ds_read_b128 v[52:55], v225 offset:32768
	ds_read_b128 v[12:15], v225 offset:32784
	global_load_dwordx4 v[96:99], v[0:1], off offset:128
	global_load_dwordx4 v[100:103], v[0:1], off offset:192
	global_load_dwordx4 v[104:107], v[2:3], off offset:128
	global_load_dwordx4 v[108:111], v[2:3], off offset:192
	global_load_dwordx4 v[112:115], v[4:5], off offset:128
	global_load_dwordx4 v[116:119], v[4:5], off offset:192
	global_load_dwordx4 v[120:123], v[6:7], off offset:128
	global_load_dwordx4 v[124:127], v[6:7], off offset:192
	ds_read_b128 v[128:131], v70 offset:64
	ds_read_b128 v[132:135], v70
	s_waitcnt vmcnt(23) lgkmcnt(0)
	v_mfma_scale_f32_16x16x128_f8f6f4 v[22:25], v[22:25], v[132:135], 0, v187, v187 op_sel_hi:[0,0,0] cbsz:4 blgp:4
	s_waitcnt vmcnt(22)
	v_mfma_scale_f32_16x16x128_f8f6f4 v[22:25], v[26:29], v[128:131], v[22:25], v187, v187 op_sel_hi:[0,0,0] cbsz:4 blgp:4
	s_waitcnt vmcnt(21)
	v_mfma_scale_f32_16x16x128_f8f6f4 v[26:29], v[30:33], v[132:135], 0, v187, v187 op_sel_hi:[0,0,0] cbsz:4 blgp:4
	s_waitcnt vmcnt(20)
	v_mfma_scale_f32_16x16x128_f8f6f4 v[26:29], v[34:37], v[128:131], v[26:29], v187, v187 op_sel_hi:[0,0,0] cbsz:4 blgp:4
	s_waitcnt vmcnt(19)
	v_mfma_scale_f32_16x16x128_f8f6f4 v[30:33], v[38:41], v[132:135], 0, v187, v187 op_sel_hi:[0,0,0] cbsz:4 blgp:4
	s_waitcnt vmcnt(17)
	v_mfma_scale_f32_16x16x128_f8f6f4 v[34:37], v[46:49], v[132:135], 0, v187, v187 op_sel_hi:[0,0,0] cbsz:4 blgp:4
	v_mfma_scale_f32_16x16x128_f8f6f4 v[30:33], v[42:45], v[128:131], v[30:33], v187, v187 op_sel_hi:[0,0,0] cbsz:4 blgp:4
	s_waitcnt vmcnt(16)
	v_mfma_scale_f32_16x16x128_f8f6f4 v[34:37], v[56:59], v[128:131], v[34:37], v187, v187 op_sel_hi:[0,0,0] cbsz:4 blgp:4
	global_load_dwordx4 v[38:41], v[8:9], off offset:128
	global_load_dwordx4 v[42:45], v[8:9], off offset:192
	global_load_dwordx4 v[46:49], v[10:11], off offset:128
	global_load_dwordx4 v[56:59], v[10:11], off offset:192
	global_load_dwordx4 v[136:139], v[18:19], off offset:128
	global_load_dwordx4 v[140:143], v[18:19], off offset:192
	global_load_dwordx4 v[144:147], v[20:21], off offset:128
	global_load_dwordx4 v[160:163], v[20:21], off offset:192
	s_waitcnt vmcnt(23)
	v_mfma_scale_f32_16x16x128_f8f6f4 v[60:63], v[60:63], v[132:135], 0, v187, v187 op_sel_hi:[0,0,0] cbsz:4 blgp:4
	s_waitcnt vmcnt(22)
	v_mfma_scale_f32_16x16x128_f8f6f4 v[60:63], v[64:67], v[128:131], v[60:63], v187, v187 op_sel_hi:[0,0,0] cbsz:4 blgp:4
	s_waitcnt vmcnt(21)
	v_mfma_scale_f32_16x16x128_f8f6f4 v[64:67], v[72:75], v[132:135], 0, v187, v187 op_sel_hi:[0,0,0] cbsz:4 blgp:4
	s_waitcnt vmcnt(20)
	v_mfma_scale_f32_16x16x128_f8f6f4 v[64:67], v[76:79], v[128:131], v[64:67], v187, v187 op_sel_hi:[0,0,0] cbsz:4 blgp:4
	s_waitcnt vmcnt(19)
	v_mfma_scale_f32_16x16x128_f8f6f4 v[72:75], v[80:83], v[132:135], 0, v187, v187 op_sel_hi:[0,0,0] cbsz:4 blgp:4
	s_waitcnt vmcnt(17)
	v_mfma_scale_f32_16x16x128_f8f6f4 v[76:79], v[88:91], v[132:135], 0, v187, v187 op_sel_hi:[0,0,0] cbsz:4 blgp:4
	v_mfma_scale_f32_16x16x128_f8f6f4 v[72:75], v[84:87], v[128:131], v[72:75], v187, v187 op_sel_hi:[0,0,0] cbsz:4 blgp:4
	s_waitcnt vmcnt(16)
	v_mfma_scale_f32_16x16x128_f8f6f4 v[76:79], v[92:95], v[128:131], v[76:79], v187, v187 op_sel_hi:[0,0,0] cbsz:4 blgp:4
	global_load_dwordx4 v[80:83], v[0:1], off offset:256
	global_load_dwordx4 v[84:87], v[0:1], off offset:320
	global_load_dwordx4 v[88:91], v[2:3], off offset:256
	global_load_dwordx4 v[92:95], v[2:3], off offset:320
	global_load_dwordx4 v[128:131], v[4:5], off offset:256
	global_load_dwordx4 v[132:135], v[4:5], off offset:320
	global_load_dwordx4 v[164:167], v[6:7], off offset:256
	global_load_dwordx4 v[168:171], v[6:7], off offset:320
	ds_read_b128 v[172:175], v70 offset:192
	ds_read_b128 v[196:199], v70 offset:128
	s_waitcnt vmcnt(23) lgkmcnt(0)
	v_mfma_scale_f32_16x16x128_f8f6f4 v[22:25], v[96:99], v[196:199], v[22:25], v187, v187 op_sel_hi:[0,0,0] cbsz:4 blgp:4
	s_waitcnt vmcnt(21)
	v_mfma_scale_f32_16x16x128_f8f6f4 v[26:29], v[104:107], v[196:199], v[26:29], v187, v187 op_sel_hi:[0,0,0] cbsz:4 blgp:4
	s_waitcnt vmcnt(19)
	v_mfma_scale_f32_16x16x128_f8f6f4 v[30:33], v[112:115], v[196:199], v[30:33], v187, v187 op_sel_hi:[0,0,0] cbsz:4 blgp:4
	s_waitcnt vmcnt(17)
	v_mfma_scale_f32_16x16x128_f8f6f4 v[34:37], v[120:123], v[196:199], v[34:37], v187, v187 op_sel_hi:[0,0,0] cbsz:4 blgp:4
	v_mfma_scale_f32_16x16x128_f8f6f4 v[22:25], v[100:103], v[172:175], v[22:25], v187, v187 op_sel_hi:[0,0,0] cbsz:4 blgp:4
	v_mfma_scale_f32_16x16x128_f8f6f4 v[26:29], v[108:111], v[172:175], v[26:29], v187, v187 op_sel_hi:[0,0,0] cbsz:4 blgp:4
	v_mfma_scale_f32_16x16x128_f8f6f4 v[30:33], v[116:119], v[172:175], v[30:33], v187, v187 op_sel_hi:[0,0,0] cbsz:4 blgp:4
	s_waitcnt vmcnt(16)
	v_mfma_scale_f32_16x16x128_f8f6f4 v[34:37], v[124:127], v[172:175], v[34:37], v187, v187 op_sel_hi:[0,0,0] cbsz:4 blgp:4
	global_load_dwordx4 v[96:99], v[8:9], off offset:256
	global_load_dwordx4 v[100:103], v[8:9], off offset:320
	global_load_dwordx4 v[104:107], v[10:11], off offset:256
	global_load_dwordx4 v[108:111], v[10:11], off offset:320
	global_load_dwordx4 v[112:115], v[18:19], off offset:256
	global_load_dwordx4 v[116:119], v[18:19], off offset:320
	global_load_dwordx4 v[120:123], v[20:21], off offset:256
	global_load_dwordx4 v[124:127], v[20:21], off offset:320
	s_waitcnt vmcnt(23)
	v_mfma_scale_f32_16x16x128_f8f6f4 v[38:41], v[38:41], v[196:199], v[60:63], v187, v187 op_sel_hi:[0,0,0] cbsz:4 blgp:4
	s_waitcnt vmcnt(22)
	v_mfma_scale_f32_16x16x128_f8f6f4 v[38:41], v[42:45], v[172:175], v[38:41], v187, v187 op_sel_hi:[0,0,0] cbsz:4 blgp:4
	s_waitcnt vmcnt(21)
	v_mfma_scale_f32_16x16x128_f8f6f4 v[42:45], v[46:49], v[196:199], v[64:67], v187, v187 op_sel_hi:[0,0,0] cbsz:4 blgp:4
	s_waitcnt vmcnt(20)
	v_mfma_scale_f32_16x16x128_f8f6f4 v[42:45], v[56:59], v[172:175], v[42:45], v187, v187 op_sel_hi:[0,0,0] cbsz:4 blgp:4
	s_waitcnt vmcnt(19)
	v_mfma_scale_f32_16x16x128_f8f6f4 v[46:49], v[136:139], v[196:199], v[72:75], v187, v187 op_sel_hi:[0,0,0] cbsz:4 blgp:4
	s_waitcnt vmcnt(17)
	v_mfma_scale_f32_16x16x128_f8f6f4 v[56:59], v[144:147], v[196:199], v[76:79], v187, v187 op_sel_hi:[0,0,0] cbsz:4 blgp:4
	v_mfma_scale_f32_16x16x128_f8f6f4 v[46:49], v[140:143], v[172:175], v[46:49], v187, v187 op_sel_hi:[0,0,0] cbsz:4 blgp:4
	s_waitcnt vmcnt(16)
	v_mfma_scale_f32_16x16x128_f8f6f4 v[56:59], v[160:163], v[172:175], v[56:59], v187, v187 op_sel_hi:[0,0,0] cbsz:4 blgp:4
	global_load_dwordx4 v[60:63], v[0:1], off offset:384
	global_load_dwordx4 v[64:67], v[0:1], off offset:448
	global_load_dwordx4 v[72:75], v[2:3], off offset:384
	global_load_dwordx4 v[76:79], v[2:3], off offset:448
	global_load_dwordx4 v[136:139], v[4:5], off offset:384
	global_load_dwordx4 v[140:143], v[4:5], off offset:448
	global_load_dwordx4 v[144:147], v[6:7], off offset:384
	global_load_dwordx4 v[160:163], v[6:7], off offset:448
	ds_read_b128 v[172:175], v70 offset:320
	ds_read_b128 v[196:199], v70 offset:256
	s_waitcnt vmcnt(23) lgkmcnt(0)
	v_mfma_scale_f32_16x16x128_f8f6f4 v[22:25], v[80:83], v[196:199], v[22:25], v187, v187 op_sel_hi:[0,0,0] cbsz:4 blgp:4
	s_waitcnt vmcnt(21)
	v_mfma_scale_f32_16x16x128_f8f6f4 v[26:29], v[88:91], v[196:199], v[26:29], v187, v187 op_sel_hi:[0,0,0] cbsz:4 blgp:4
	s_waitcnt vmcnt(19)
	v_mfma_scale_f32_16x16x128_f8f6f4 v[30:33], v[128:131], v[196:199], v[30:33], v187, v187 op_sel_hi:[0,0,0] cbsz:4 blgp:4
	s_waitcnt vmcnt(17)
	v_mfma_scale_f32_16x16x128_f8f6f4 v[34:37], v[164:167], v[196:199], v[34:37], v187, v187 op_sel_hi:[0,0,0] cbsz:4 blgp:4
	v_mfma_scale_f32_16x16x128_f8f6f4 v[22:25], v[84:87], v[172:175], v[22:25], v187, v187 op_sel_hi:[0,0,0] cbsz:4 blgp:4
	v_mfma_scale_f32_16x16x128_f8f6f4 v[26:29], v[92:95], v[172:175], v[26:29], v187, v187 op_sel_hi:[0,0,0] cbsz:4 blgp:4
	v_mfma_scale_f32_16x16x128_f8f6f4 v[30:33], v[132:135], v[172:175], v[30:33], v187, v187 op_sel_hi:[0,0,0] cbsz:4 blgp:4
	s_waitcnt vmcnt(16)
	v_mfma_scale_f32_16x16x128_f8f6f4 v[34:37], v[168:171], v[172:175], v[34:37], v187, v187 op_sel_hi:[0,0,0] cbsz:4 blgp:4
	global_load_dwordx4 v[80:83], v[8:9], off offset:384
	global_load_dwordx4 v[84:87], v[8:9], off offset:448
	global_load_dwordx4 v[88:91], v[10:11], off offset:384
	global_load_dwordx4 v[92:95], v[10:11], off offset:448
	global_load_dwordx4 v[128:131], v[18:19], off offset:384
	global_load_dwordx4 v[132:135], v[18:19], off offset:448
	global_load_dwordx4 v[164:167], v[20:21], off offset:384
	global_load_dwordx4 v[168:171], v[20:21], off offset:448
	s_waitcnt vmcnt(23)
	v_mfma_scale_f32_16x16x128_f8f6f4 v[38:41], v[96:99], v[196:199], v[38:41], v187, v187 op_sel_hi:[0,0,0] cbsz:4 blgp:4
	s_waitcnt vmcnt(21)
	v_mfma_scale_f32_16x16x128_f8f6f4 v[42:45], v[104:107], v[196:199], v[42:45], v187, v187 op_sel_hi:[0,0,0] cbsz:4 blgp:4
	s_waitcnt vmcnt(19)
	v_mfma_scale_f32_16x16x128_f8f6f4 v[46:49], v[112:115], v[196:199], v[46:49], v187, v187 op_sel_hi:[0,0,0] cbsz:4 blgp:4
	s_waitcnt vmcnt(17)
	v_mfma_scale_f32_16x16x128_f8f6f4 v[56:59], v[120:123], v[196:199], v[56:59], v187, v187 op_sel_hi:[0,0,0] cbsz:4 blgp:4
	v_mfma_scale_f32_16x16x128_f8f6f4 v[38:41], v[100:103], v[172:175], v[38:41], v187, v187 op_sel_hi:[0,0,0] cbsz:4 blgp:4
	v_mfma_scale_f32_16x16x128_f8f6f4 v[42:45], v[108:111], v[172:175], v[42:45], v187, v187 op_sel_hi:[0,0,0] cbsz:4 blgp:4
	v_mfma_scale_f32_16x16x128_f8f6f4 v[46:49], v[116:119], v[172:175], v[46:49], v187, v187 op_sel_hi:[0,0,0] cbsz:4 blgp:4
	s_waitcnt vmcnt(16)
	v_mfma_scale_f32_16x16x128_f8f6f4 v[56:59], v[124:127], v[172:175], v[56:59], v187, v187 op_sel_hi:[0,0,0] cbsz:4 blgp:4
	global_load_dwordx4 v[96:99], v[0:1], off offset:512
	global_load_dwordx4 v[100:103], v[0:1], off offset:576
	global_load_dwordx4 v[104:107], v[2:3], off offset:512
	global_load_dwordx4 v[108:111], v[2:3], off offset:576
	global_load_dwordx4 v[112:115], v[4:5], off offset:512
	global_load_dwordx4 v[116:119], v[4:5], off offset:576
	global_load_dwordx4 v[120:123], v[6:7], off offset:512
	global_load_dwordx4 v[124:127], v[6:7], off offset:576
	ds_read_b128 v[172:175], v70 offset:448
	ds_read_b128 v[196:199], v70 offset:384
	s_waitcnt vmcnt(23) lgkmcnt(0)
	v_mfma_scale_f32_16x16x128_f8f6f4 v[22:25], v[60:63], v[196:199], v[22:25], v187, v187 op_sel_hi:[0,0,0] cbsz:4 blgp:4
	s_waitcnt vmcnt(21)
	v_mfma_scale_f32_16x16x128_f8f6f4 v[26:29], v[72:75], v[196:199], v[26:29], v187, v187 op_sel_hi:[0,0,0] cbsz:4 blgp:4
	s_waitcnt vmcnt(19)
	v_mfma_scale_f32_16x16x128_f8f6f4 v[30:33], v[136:139], v[196:199], v[30:33], v187, v187 op_sel_hi:[0,0,0] cbsz:4 blgp:4
	s_waitcnt vmcnt(17)
	v_mfma_scale_f32_16x16x128_f8f6f4 v[34:37], v[144:147], v[196:199], v[34:37], v187, v187 op_sel_hi:[0,0,0] cbsz:4 blgp:4
	v_mfma_scale_f32_16x16x128_f8f6f4 v[22:25], v[64:67], v[172:175], v[22:25], v187, v187 op_sel_hi:[0,0,0] cbsz:4 blgp:4
	v_mfma_scale_f32_16x16x128_f8f6f4 v[26:29], v[76:79], v[172:175], v[26:29], v187, v187 op_sel_hi:[0,0,0] cbsz:4 blgp:4
	v_mfma_scale_f32_16x16x128_f8f6f4 v[30:33], v[140:143], v[172:175], v[30:33], v187, v187 op_sel_hi:[0,0,0] cbsz:4 blgp:4
	s_waitcnt vmcnt(16)
	v_mfma_scale_f32_16x16x128_f8f6f4 v[34:37], v[160:163], v[172:175], v[34:37], v187, v187 op_sel_hi:[0,0,0] cbsz:4 blgp:4
	global_load_dwordx4 v[60:63], v[8:9], off offset:512
	global_load_dwordx4 v[64:67], v[8:9], off offset:576
	global_load_dwordx4 v[72:75], v[10:11], off offset:512
	global_load_dwordx4 v[76:79], v[10:11], off offset:576
	global_load_dwordx4 v[136:139], v[18:19], off offset:512
	global_load_dwordx4 v[140:143], v[18:19], off offset:576
	global_load_dwordx4 v[144:147], v[20:21], off offset:512
	global_load_dwordx4 v[160:163], v[20:21], off offset:576
	s_waitcnt vmcnt(23)
	v_mfma_scale_f32_16x16x128_f8f6f4 v[38:41], v[80:83], v[196:199], v[38:41], v187, v187 op_sel_hi:[0,0,0] cbsz:4 blgp:4
	s_waitcnt vmcnt(21)
	v_mfma_scale_f32_16x16x128_f8f6f4 v[42:45], v[88:91], v[196:199], v[42:45], v187, v187 op_sel_hi:[0,0,0] cbsz:4 blgp:4
	s_waitcnt vmcnt(19)
	v_mfma_scale_f32_16x16x128_f8f6f4 v[46:49], v[128:131], v[196:199], v[46:49], v187, v187 op_sel_hi:[0,0,0] cbsz:4 blgp:4
	s_waitcnt vmcnt(17)
	v_mfma_scale_f32_16x16x128_f8f6f4 v[56:59], v[164:167], v[196:199], v[56:59], v187, v187 op_sel_hi:[0,0,0] cbsz:4 blgp:4
	v_mfma_scale_f32_16x16x128_f8f6f4 v[38:41], v[84:87], v[172:175], v[38:41], v187, v187 op_sel_hi:[0,0,0] cbsz:4 blgp:4
	v_mfma_scale_f32_16x16x128_f8f6f4 v[42:45], v[92:95], v[172:175], v[42:45], v187, v187 op_sel_hi:[0,0,0] cbsz:4 blgp:4
	v_mfma_scale_f32_16x16x128_f8f6f4 v[46:49], v[132:135], v[172:175], v[46:49], v187, v187 op_sel_hi:[0,0,0] cbsz:4 blgp:4
	s_waitcnt vmcnt(16)
	v_mfma_scale_f32_16x16x128_f8f6f4 v[56:59], v[168:171], v[172:175], v[56:59], v187, v187 op_sel_hi:[0,0,0] cbsz:4 blgp:4
	global_load_dwordx4 v[80:83], v[0:1], off offset:640
	global_load_dwordx4 v[84:87], v[0:1], off offset:704
	global_load_dwordx4 v[88:91], v[2:3], off offset:640
	global_load_dwordx4 v[92:95], v[2:3], off offset:704
	global_load_dwordx4 v[128:131], v[4:5], off offset:640
	global_load_dwordx4 v[132:135], v[4:5], off offset:704
	global_load_dwordx4 v[164:167], v[6:7], off offset:640
	global_load_dwordx4 v[168:171], v[6:7], off offset:704
	ds_read_b128 v[172:175], v70 offset:576
	ds_read_b128 v[196:199], v70 offset:512
	s_waitcnt vmcnt(23) lgkmcnt(0)
	v_mfma_scale_f32_16x16x128_f8f6f4 v[22:25], v[96:99], v[196:199], v[22:25], v187, v187 op_sel_hi:[0,0,0] cbsz:4 blgp:4
	s_waitcnt vmcnt(21)
	v_mfma_scale_f32_16x16x128_f8f6f4 v[26:29], v[104:107], v[196:199], v[26:29], v187, v187 op_sel_hi:[0,0,0] cbsz:4 blgp:4
	s_waitcnt vmcnt(19)
	v_mfma_scale_f32_16x16x128_f8f6f4 v[30:33], v[112:115], v[196:199], v[30:33], v187, v187 op_sel_hi:[0,0,0] cbsz:4 blgp:4
	s_waitcnt vmcnt(17)
	v_mfma_scale_f32_16x16x128_f8f6f4 v[34:37], v[120:123], v[196:199], v[34:37], v187, v187 op_sel_hi:[0,0,0] cbsz:4 blgp:4
	v_mfma_scale_f32_16x16x128_f8f6f4 v[22:25], v[100:103], v[172:175], v[22:25], v187, v187 op_sel_hi:[0,0,0] cbsz:4 blgp:4
	v_mfma_scale_f32_16x16x128_f8f6f4 v[26:29], v[108:111], v[172:175], v[26:29], v187, v187 op_sel_hi:[0,0,0] cbsz:4 blgp:4
	v_mfma_scale_f32_16x16x128_f8f6f4 v[30:33], v[116:119], v[172:175], v[30:33], v187, v187 op_sel_hi:[0,0,0] cbsz:4 blgp:4
	s_waitcnt vmcnt(16)
	v_mfma_scale_f32_16x16x128_f8f6f4 v[34:37], v[124:127], v[172:175], v[34:37], v187, v187 op_sel_hi:[0,0,0] cbsz:4 blgp:4
	global_load_dwordx4 v[96:99], v[8:9], off offset:640
	global_load_dwordx4 v[100:103], v[8:9], off offset:704
	global_load_dwordx4 v[104:107], v[10:11], off offset:640
	global_load_dwordx4 v[108:111], v[10:11], off offset:704
	global_load_dwordx4 v[112:115], v[18:19], off offset:640
	global_load_dwordx4 v[116:119], v[18:19], off offset:704
	global_load_dwordx4 v[120:123], v[20:21], off offset:640
	global_load_dwordx4 v[124:127], v[20:21], off offset:704
	s_waitcnt vmcnt(23)
	v_mfma_scale_f32_16x16x128_f8f6f4 v[38:41], v[60:63], v[196:199], v[38:41], v187, v187 op_sel_hi:[0,0,0] cbsz:4 blgp:4
	s_waitcnt vmcnt(21)
	v_mfma_scale_f32_16x16x128_f8f6f4 v[42:45], v[72:75], v[196:199], v[42:45], v187, v187 op_sel_hi:[0,0,0] cbsz:4 blgp:4
	s_waitcnt vmcnt(19)
	v_mfma_scale_f32_16x16x128_f8f6f4 v[46:49], v[136:139], v[196:199], v[46:49], v187, v187 op_sel_hi:[0,0,0] cbsz:4 blgp:4
	s_waitcnt vmcnt(17)
	v_mfma_scale_f32_16x16x128_f8f6f4 v[56:59], v[144:147], v[196:199], v[56:59], v187, v187 op_sel_hi:[0,0,0] cbsz:4 blgp:4
	v_mfma_scale_f32_16x16x128_f8f6f4 v[38:41], v[64:67], v[172:175], v[38:41], v187, v187 op_sel_hi:[0,0,0] cbsz:4 blgp:4
	v_mfma_scale_f32_16x16x128_f8f6f4 v[42:45], v[76:79], v[172:175], v[42:45], v187, v187 op_sel_hi:[0,0,0] cbsz:4 blgp:4
	v_mfma_scale_f32_16x16x128_f8f6f4 v[46:49], v[140:143], v[172:175], v[46:49], v187, v187 op_sel_hi:[0,0,0] cbsz:4 blgp:4
	s_waitcnt vmcnt(16)
	v_mfma_scale_f32_16x16x128_f8f6f4 v[56:59], v[160:163], v[172:175], v[56:59], v187, v187 op_sel_hi:[0,0,0] cbsz:4 blgp:4
	global_load_dwordx4 v[60:63], v[0:1], off offset:768
	global_load_dwordx4 v[64:67], v[0:1], off offset:832
	global_load_dwordx4 v[72:75], v[2:3], off offset:768
	global_load_dwordx4 v[76:79], v[2:3], off offset:832
	global_load_dwordx4 v[136:139], v[4:5], off offset:768
	global_load_dwordx4 v[140:143], v[4:5], off offset:832
	global_load_dwordx4 v[144:147], v[6:7], off offset:768
	global_load_dwordx4 v[160:163], v[6:7], off offset:832
	ds_read_b128 v[172:175], v70 offset:704
	ds_read_b128 v[196:199], v70 offset:640
	s_waitcnt vmcnt(23) lgkmcnt(0)
	v_mfma_scale_f32_16x16x128_f8f6f4 v[22:25], v[80:83], v[196:199], v[22:25], v187, v187 op_sel_hi:[0,0,0] cbsz:4 blgp:4
	s_waitcnt vmcnt(21)
	v_mfma_scale_f32_16x16x128_f8f6f4 v[26:29], v[88:91], v[196:199], v[26:29], v187, v187 op_sel_hi:[0,0,0] cbsz:4 blgp:4
	s_waitcnt vmcnt(19)
	v_mfma_scale_f32_16x16x128_f8f6f4 v[30:33], v[128:131], v[196:199], v[30:33], v187, v187 op_sel_hi:[0,0,0] cbsz:4 blgp:4
	s_waitcnt vmcnt(17)
	v_mfma_scale_f32_16x16x128_f8f6f4 v[34:37], v[164:167], v[196:199], v[34:37], v187, v187 op_sel_hi:[0,0,0] cbsz:4 blgp:4
	v_mfma_scale_f32_16x16x128_f8f6f4 v[22:25], v[84:87], v[172:175], v[22:25], v187, v187 op_sel_hi:[0,0,0] cbsz:4 blgp:4
	v_mfma_scale_f32_16x16x128_f8f6f4 v[26:29], v[92:95], v[172:175], v[26:29], v187, v187 op_sel_hi:[0,0,0] cbsz:4 blgp:4
	v_mfma_scale_f32_16x16x128_f8f6f4 v[30:33], v[132:135], v[172:175], v[30:33], v187, v187 op_sel_hi:[0,0,0] cbsz:4 blgp:4
	s_waitcnt vmcnt(16)
	v_mfma_scale_f32_16x16x128_f8f6f4 v[34:37], v[168:171], v[172:175], v[34:37], v187, v187 op_sel_hi:[0,0,0] cbsz:4 blgp:4
	global_load_dwordx4 v[80:83], v[8:9], off offset:768
	global_load_dwordx4 v[84:87], v[8:9], off offset:832
	global_load_dwordx4 v[88:91], v[10:11], off offset:768
	global_load_dwordx4 v[92:95], v[10:11], off offset:832
	global_load_dwordx4 v[128:131], v[18:19], off offset:768
	global_load_dwordx4 v[132:135], v[18:19], off offset:832
	global_load_dwordx4 v[164:167], v[20:21], off offset:768
	global_load_dwordx4 v[168:171], v[20:21], off offset:832
	s_waitcnt vmcnt(23)
	v_mfma_scale_f32_16x16x128_f8f6f4 v[38:41], v[96:99], v[196:199], v[38:41], v187, v187 op_sel_hi:[0,0,0] cbsz:4 blgp:4
	s_waitcnt vmcnt(21)
	v_mfma_scale_f32_16x16x128_f8f6f4 v[42:45], v[104:107], v[196:199], v[42:45], v187, v187 op_sel_hi:[0,0,0] cbsz:4 blgp:4
	s_waitcnt vmcnt(19)
	v_mfma_scale_f32_16x16x128_f8f6f4 v[46:49], v[112:115], v[196:199], v[46:49], v187, v187 op_sel_hi:[0,0,0] cbsz:4 blgp:4
	s_waitcnt vmcnt(17)
	v_mfma_scale_f32_16x16x128_f8f6f4 v[56:59], v[120:123], v[196:199], v[56:59], v187, v187 op_sel_hi:[0,0,0] cbsz:4 blgp:4
	v_mfma_scale_f32_16x16x128_f8f6f4 v[38:41], v[100:103], v[172:175], v[38:41], v187, v187 op_sel_hi:[0,0,0] cbsz:4 blgp:4
	v_mfma_scale_f32_16x16x128_f8f6f4 v[42:45], v[108:111], v[172:175], v[42:45], v187, v187 op_sel_hi:[0,0,0] cbsz:4 blgp:4
	v_mfma_scale_f32_16x16x128_f8f6f4 v[46:49], v[116:119], v[172:175], v[46:49], v187, v187 op_sel_hi:[0,0,0] cbsz:4 blgp:4
	s_waitcnt vmcnt(16)
	v_mfma_scale_f32_16x16x128_f8f6f4 v[56:59], v[124:127], v[172:175], v[56:59], v187, v187 op_sel_hi:[0,0,0] cbsz:4 blgp:4
	global_load_dwordx4 v[96:99], v[0:1], off offset:896
	global_load_dwordx4 v[100:103], v[0:1], off offset:960
	global_load_dwordx4 v[104:107], v[2:3], off offset:896
	global_load_dwordx4 v[108:111], v[2:3], off offset:960
	global_load_dwordx4 v[112:115], v[4:5], off offset:896
	global_load_dwordx4 v[116:119], v[4:5], off offset:960
	global_load_dwordx4 v[120:123], v[6:7], off offset:896
	global_load_dwordx4 v[124:127], v[6:7], off offset:960
	ds_read_b128 v[0:3], v70 offset:832
	ds_read_b128 v[4:7], v70 offset:768
	s_waitcnt vmcnt(23) lgkmcnt(0)
	v_mfma_scale_f32_16x16x128_f8f6f4 v[22:25], v[60:63], v[4:7], v[22:25], v187, v187 op_sel_hi:[0,0,0] cbsz:4 blgp:4
	s_waitcnt vmcnt(22)
	v_mfma_scale_f32_16x16x128_f8f6f4 v[172:175], v[64:67], v[0:3], v[22:25], v187, v187 op_sel_hi:[0,0,0] cbsz:4 blgp:4
	s_waitcnt vmcnt(21)
	v_mfma_scale_f32_16x16x128_f8f6f4 v[22:25], v[72:75], v[4:7], v[26:29], v187, v187 op_sel_hi:[0,0,0] cbsz:4 blgp:4
	s_waitcnt vmcnt(20)
	v_mfma_scale_f32_16x16x128_f8f6f4 v[72:75], v[76:79], v[0:3], v[22:25], v187, v187 op_sel_hi:[0,0,0] cbsz:4 blgp:4
	s_waitcnt vmcnt(19)
	v_mfma_scale_f32_16x16x128_f8f6f4 v[22:25], v[136:139], v[4:7], v[30:33], v187, v187 op_sel_hi:[0,0,0] cbsz:4 blgp:4
	s_waitcnt vmcnt(18)
	v_mfma_scale_f32_16x16x128_f8f6f4 v[76:79], v[140:143], v[0:3], v[22:25], v187, v187 op_sel_hi:[0,0,0] cbsz:4 blgp:4
	s_waitcnt vmcnt(17)
	v_mfma_scale_f32_16x16x128_f8f6f4 v[22:25], v[144:147], v[4:7], v[34:37], v187, v187 op_sel_hi:[0,0,0] cbsz:4 blgp:4
	s_waitcnt vmcnt(16)
	v_mfma_scale_f32_16x16x128_f8f6f4 v[160:163], v[160:163], v[0:3], v[22:25], v187, v187 op_sel_hi:[0,0,0] cbsz:4 blgp:4
	global_load_dwordx4 v[196:199], v[8:9], off offset:896
	global_load_dwordx4 v[200:203], v[8:9], off offset:960
	global_load_dwordx4 v[204:207], v[10:11], off offset:896
	global_load_dwordx4 v[208:211], v[10:11], off offset:960
	global_load_dwordx4 v[226:229], v[18:19], off offset:896
	global_load_dwordx4 v[230:233], v[18:19], off offset:960
	global_load_dwordx4 v[234:237], v[20:21], off offset:896
	global_load_dwordx4 v[238:241], v[20:21], off offset:960
	s_waitcnt vmcnt(23)
	v_mfma_scale_f32_16x16x128_f8f6f4 v[8:11], v[80:83], v[4:7], v[38:41], v187, v187 op_sel_hi:[0,0,0] cbsz:4 blgp:4
	s_waitcnt vmcnt(22)
	v_mfma_scale_f32_16x16x128_f8f6f4 v[80:83], v[84:87], v[0:3], v[8:11], v187, v187 op_sel_hi:[0,0,0] cbsz:4 blgp:4
	s_waitcnt vmcnt(21)
	v_mfma_scale_f32_16x16x128_f8f6f4 v[8:11], v[88:91], v[4:7], v[42:45], v187, v187 op_sel_hi:[0,0,0] cbsz:4 blgp:4
	s_waitcnt vmcnt(20)
	v_mfma_scale_f32_16x16x128_f8f6f4 v[84:87], v[92:95], v[0:3], v[8:11], v187, v187 op_sel_hi:[0,0,0] cbsz:4 blgp:4
	s_waitcnt vmcnt(19)
	v_mfma_scale_f32_16x16x128_f8f6f4 v[8:11], v[128:131], v[4:7], v[46:49], v187, v187 op_sel_hi:[0,0,0] cbsz:4 blgp:4
	s_waitcnt vmcnt(17)
	v_mfma_scale_f32_16x16x128_f8f6f4 v[4:7], v[164:167], v[4:7], v[56:59], v187, v187 op_sel_hi:[0,0,0] cbsz:4 blgp:4
	v_mfma_scale_f32_16x16x128_f8f6f4 v[88:91], v[132:135], v[0:3], v[8:11], v187, v187 op_sel_hi:[0,0,0] cbsz:4 blgp:4
	s_waitcnt vmcnt(16)
	v_mfma_scale_f32_16x16x128_f8f6f4 v[92:95], v[168:171], v[0:3], v[4:7], v187, v187 op_sel_hi:[0,0,0] cbsz:4 blgp:4
	v_mov_b32_e32 v0, v52
	v_mov_b32_e32 v1, v16
	v_mov_b32_e32 v22, v53
	v_mov_b32_e32 v23, v16
	v_mov_b32_e32 v38, v54
	v_mov_b32_e32 v39, v16
	v_mov_b32_e32 v54, v55
	v_mov_b32_e32 v55, v16
	v_lshlrev_b64 v[0:1], 10, v[0:1]
	v_lshlrev_b64 v[22:23], 10, v[22:23]
	v_lshlrev_b64 v[38:39], 10, v[38:39]
	v_lshlrev_b64 v[54:55], 10, v[54:55]
	v_lshl_add_u64 v[18:19], v[182:183], 0, v[0:1]
	v_lshl_add_u64 v[34:35], v[182:183], 0, v[22:23]
	v_lshl_add_u64 v[50:51], v[182:183], 0, v[38:39]
	v_lshl_add_u64 v[66:67], v[182:183], 0, v[54:55]
	global_load_dwordx4 v[0:3], v[18:19], off
	global_load_dwordx4 v[4:7], v[18:19], off offset:256
	global_load_dwordx4 v[8:11], v[18:19], off offset:512
	s_nop 0
	global_load_dwordx4 v[18:21], v[18:19], off offset:768
	s_nop 0
	global_load_dwordx4 v[22:25], v[34:35], off
	global_load_dwordx4 v[26:29], v[34:35], off offset:256
	global_load_dwordx4 v[30:33], v[34:35], off offset:512
	s_nop 0
	global_load_dwordx4 v[34:37], v[34:35], off offset:768
	s_nop 0
	global_load_dwordx4 v[38:41], v[50:51], off
	global_load_dwordx4 v[42:45], v[50:51], off offset:256
	global_load_dwordx4 v[46:49], v[50:51], off offset:512
	s_nop 0
	global_load_dwordx4 v[50:53], v[50:51], off offset:768
	s_nop 0
	global_load_dwordx4 v[54:57], v[66:67], off
	global_load_dwordx4 v[58:61], v[66:67], off offset:256
	global_load_dwordx4 v[62:65], v[66:67], off offset:512
	s_nop 0
	global_load_dwordx4 v[66:69], v[66:67], off offset:768
	ds_read_b128 v[164:167], v70 offset:960
	ds_read_b128 v[168:171], v70 offset:896
	s_waitcnt vmcnt(29) lgkmcnt(0)
	v_mfma_scale_f32_16x16x128_f8f6f4 v[70:73], v[104:107], v[168:171], v[72:75], v187, v187 op_sel_hi:[0,0,0] cbsz:4 blgp:4
	s_waitcnt vmcnt(28)
	v_mfma_scale_f32_16x16x128_f8f6f4 v[142:145], v[108:111], v[164:167], v[70:73], v187, v187 op_sel_hi:[0,0,0] cbsz:4 blgp:4
	s_waitcnt vmcnt(27)
	v_mfma_scale_f32_16x16x128_f8f6f4 v[70:73], v[112:115], v[168:171], v[76:79], v187, v187 op_sel_hi:[0,0,0] cbsz:4 blgp:4
	v_mfma_scale_f32_16x16x128_f8f6f4 v[96:99], v[96:99], v[168:171], v[172:175], v187, v187 op_sel_hi:[0,0,0] cbsz:4 blgp:4
	s_waitcnt vmcnt(26)
	v_mfma_scale_f32_16x16x128_f8f6f4 v[138:141], v[116:119], v[164:167], v[70:73], v187, v187 op_sel_hi:[0,0,0] cbsz:4 blgp:4
	s_waitcnt vmcnt(25)
	v_mfma_scale_f32_16x16x128_f8f6f4 v[70:73], v[120:123], v[168:171], v[160:163], v187, v187 op_sel_hi:[0,0,0] cbsz:4 blgp:4
	v_mfma_scale_f32_16x16x128_f8f6f4 v[146:149], v[100:103], v[164:167], v[96:99], v187, v187 op_sel_hi:[0,0,0] cbsz:4 blgp:4
	s_waitcnt vmcnt(24)
	v_mfma_scale_f32_16x16x128_f8f6f4 v[134:137], v[124:127], v[164:167], v[70:73], v187, v187 op_sel_hi:[0,0,0] cbsz:4 blgp:4
	s_waitcnt vmcnt(23)
	v_mfma_scale_f32_16x16x128_f8f6f4 v[70:73], v[196:199], v[168:171], v[80:83], v187, v187 op_sel_hi:[0,0,0] cbsz:4 blgp:4
	s_waitcnt vmcnt(22)
	v_mfma_scale_f32_16x16x128_f8f6f4 v[130:133], v[200:203], v[164:167], v[70:73], v187, v187 op_sel_hi:[0,0,0] cbsz:4 blgp:4
	s_waitcnt vmcnt(21)
	v_mfma_scale_f32_16x16x128_f8f6f4 v[70:73], v[204:207], v[168:171], v[84:87], v187, v187 op_sel_hi:[0,0,0] cbsz:4 blgp:4
	s_waitcnt vmcnt(20)
	v_mfma_scale_f32_16x16x128_f8f6f4 v[126:129], v[208:211], v[164:167], v[70:73], v187, v187 op_sel_hi:[0,0,0] cbsz:4 blgp:4
	s_waitcnt vmcnt(19)
	v_mfma_scale_f32_16x16x128_f8f6f4 v[70:73], v[226:229], v[168:171], v[88:91], v187, v187 op_sel_hi:[0,0,0] cbsz:4 blgp:4
	s_waitcnt vmcnt(18)
	v_mfma_scale_f32_16x16x128_f8f6f4 v[122:125], v[230:233], v[164:167], v[70:73], v187, v187 op_sel_hi:[0,0,0] cbsz:4 blgp:4
	s_waitcnt vmcnt(17)
	v_mfma_scale_f32_16x16x128_f8f6f4 v[70:73], v[234:237], v[168:171], v[92:95], v187, v187 op_sel_hi:[0,0,0] cbsz:4 blgp:4
	s_waitcnt vmcnt(16)
	v_mfma_scale_f32_16x16x128_f8f6f4 v[118:121], v[238:241], v[164:167], v[70:73], v187, v187 op_sel_hi:[0,0,0] cbsz:4 blgp:4
	s_nop 5
	v_mov_b32_e32 v70, v12
	v_mov_b32_e32 v71, v16
	v_mov_b32_e32 v12, v13
	v_mov_b32_e32 v13, v16
	v_lshlrev_b64 v[70:71], 10, v[70:71]
	v_lshlrev_b64 v[12:13], 10, v[12:13]
	v_lshl_add_u64 v[82:83], v[182:183], 0, v[70:71]
	v_lshl_add_u64 v[12:13], v[182:183], 0, v[12:13]
	global_load_dwordx4 v[70:73], v[82:83], off
	global_load_dwordx4 v[74:77], v[82:83], off offset:256
	global_load_dwordx4 v[78:81], v[82:83], off offset:512
	s_nop 0
	global_load_dwordx4 v[82:85], v[82:83], off offset:768
	s_nop 0
	global_load_dwordx4 v[86:89], v[12:13], off
	global_load_dwordx4 v[90:93], v[12:13], off offset:256
	global_load_dwordx4 v[94:97], v[12:13], off offset:512
	global_load_dwordx4 v[98:101], v[12:13], off offset:768
	v_mov_b32_e32 v12, v14
	v_mov_b32_e32 v13, v16
	v_lshlrev_b64 v[12:13], 10, v[12:13]
	v_lshl_add_u64 v[12:13], v[182:183], 0, v[12:13]
	global_load_dwordx4 v[102:105], v[12:13], off
	global_load_dwordx4 v[106:109], v[12:13], off offset:256
	global_load_dwordx4 v[110:113], v[12:13], off offset:512
	global_load_dwordx4 v[114:117], v[12:13], off offset:768
	v_cmp_lt_i32_e32 vcc, 0, v154
	v_mov_b32_e32 v12, 0x3d321643
	s_and_saveexec_b64 s[10:11], vcc
	s_cbranch_execz .LBB0_738
	v_cmp_ne_u32_e32 vcc, 1, v154
	s_and_saveexec_b64 s[12:13], vcc
	s_xor_b64 s[12:13], exec, s[12:13]
	v_cmp_eq_u32_e32 vcc, 2, v154
	v_mov_b32_e32 v12, 0x3a321643
	v_mov_b32_e32 v13, 0x3b321643
	v_cndmask_b32_e32 v12, v12, v13, vcc
	s_andn2_saveexec_b64 s[12:13], s[12:13]
	v_mov_b32_e32 v12, 0x3c321643
	s_or_b64 exec, exec, s[12:13]
